# SwiGLU epilogue: rs^2/(1+e) computed as rcp(e/rs^2 + 1/rs^2) (pk_fma instead of pk_add, the pk_mul by rs^2 after the rcp removed: 27 packed multiplies fewer per tile and wave)
# baseline (speedup 1.0000x reference)
.LBB0_708:
	v_lshl_add_u32 v154, s40, 10, v150
	ds_read2_b32 v[156:157], v154 offset1:16
	v_pk_mul_f32 v[120:121], v[124:125], v[120:121]
	v_pk_mul_f32 v[122:123], v[126:127], v[122:123]
	v_lshl_or_b32 v158, s41, 7, v149
	v_pk_mul_f32 v[114:115], v[118:119], v[114:115]
	s_waitcnt lgkmcnt(0)
	v_mul_f32_e32 v160, 0xbfb8aa3b, v156
	v_pk_mul_f32 v[164:165], v[124:125], v[160:161] op_sel_hi:[1,0]
	v_pk_mul_f32 v[162:163], v[126:127], v[160:161] op_sel_hi:[1,0]
	v_exp_f32_e32 v164, v164
	v_exp_f32_e32 v165, v165
	v_exp_f32_e32 v162, v162
	v_exp_f32_e32 v163, v163
	v_mul_f32_e32 v156, v156, v156
	v_rcp_f32_e32 v232, v156
	s_nop 0
	v_pk_fma_f32 v[164:165], v[164:165], v[232:233], v[232:233] op_sel_hi:[1,0,0]
	v_ashrrev_i32_e32 v159, 31, v158
	v_pk_fma_f32 v[162:163], v[162:163], v[232:233], v[232:233] op_sel_hi:[1,0,0]
	v_rcp_f32_e32 v164, v164
	v_rcp_f32_e32 v165, v165
	v_rcp_f32_e32 v162, v162
	v_rcp_f32_e32 v163, v163
	v_pk_mul_f32 v[112:113], v[116:117], v[112:113]
	v_pk_mul_f32 v[120:121], v[120:121], v[164:165]
	v_pk_mul_f32 v[124:125], v[118:119], v[160:161] op_sel_hi:[1,0]
	v_pk_mul_f32 v[122:123], v[122:123], v[162:163]
	v_pk_mul_f32 v[126:127], v[116:117], v[160:161] op_sel_hi:[1,0]
	v_exp_f32_e32 v124, v124
	v_exp_f32_e32 v125, v125
	v_exp_f32_e32 v126, v126
	v_exp_f32_e32 v127, v127
	v_cvt_pk_bf16_f32 v120, v120, v121
	v_cvt_pk_bf16_f32 v121, v122, v123
	v_pk_fma_f32 v[122:123], v[124:125], v[232:233], v[232:233] op_sel_hi:[1,0,0]
	v_pk_fma_f32 v[124:125], v[126:127], v[232:233], v[232:233] op_sel_hi:[1,0,0]
	v_rcp_f32_e32 v122, v122
	v_rcp_f32_e32 v123, v123
	v_rcp_f32_e32 v124, v124
	v_rcp_f32_e32 v125, v125
	s_lshl_b32 s11, s18, 8
	v_pk_mul_f32 v[114:115], v[114:115], v[122:123]
	v_pk_mul_f32 v[116:117], v[124:125], 1.0 op_sel_hi:[1,0]
	v_mul_f32_e32 v124, 0xbfb8aa3b, v157
	v_cvt_pk_bf16_f32 v123, v114, v115
	v_lshlrev_b64 v[114:115], 1, v[158:159]
	v_pk_mul_f32 v[126:127], v[110:111], v[124:125] op_sel_hi:[1,0]
	v_pk_mul_f32 v[158:159], v[108:109], v[124:125] op_sel_hi:[1,0]
	v_pk_mul_f32 v[112:113], v[112:113], v[116:117]
	v_exp_f32_e32 v158, v158
	v_exp_f32_e32 v126, v126
	v_exp_f32_e32 v127, v127
	v_exp_f32_e32 v159, v159
	v_cvt_pk_bf16_f32 v122, v112, v113
	v_add_u32_e32 v116, s11, v144
	v_mov_b64_e32 v[112:113], s[76:77]
	v_mad_i64_i32 v[118:119], s[20:21], v116, s38, v[112:113]
	v_lshl_add_u64 v[118:119], v[118:119], 0, v[114:115]
	global_store_dwordx4 v[118:119], v[120:123], off nt
	v_mul_f32_e32 v118, v157, v157
	v_rcp_f32_e32 v234, v118
	s_nop 0
	v_pk_mul_f32 v[106:107], v[110:111], v[106:107]
	v_pk_fma_f32 v[120:121], v[126:127], v[234:235], v[234:235] op_sel_hi:[1,0,0]
	v_pk_fma_f32 v[122:123], v[158:159], v[234:235], v[234:235] op_sel_hi:[1,0,0]
	v_rcp_f32_e32 v120, v120
	v_rcp_f32_e32 v122, v122
	v_rcp_f32_e32 v123, v123
	v_rcp_f32_e32 v121, v121
	v_pk_mul_f32 v[104:105], v[108:109], v[104:105]
	v_pk_mul_f32 v[96:97], v[100:101], v[96:97]
	v_pk_mul_f32 v[106:107], v[106:107], v[120:121]
	v_pk_mul_f32 v[104:105], v[104:105], v[122:123]
	v_pk_mul_f32 v[108:109], v[102:103], v[124:125] op_sel_hi:[1,0]
	v_pk_mul_f32 v[110:111], v[100:101], v[124:125] op_sel_hi:[1,0]
	v_exp_f32_e32 v108, v108
	v_exp_f32_e32 v110, v110
	v_exp_f32_e32 v109, v109
	v_exp_f32_e32 v111, v111
	v_cvt_pk_bf16_f32 v104, v104, v105
	v_cvt_pk_bf16_f32 v105, v106, v107
	v_pk_fma_f32 v[106:107], v[108:109], v[234:235], v[234:235] op_sel_hi:[1,0,0]
	v_pk_fma_f32 v[108:109], v[110:111], v[234:235], v[234:235] op_sel_hi:[1,0,0]
	v_rcp_f32_e32 v106, v106
	v_rcp_f32_e32 v108, v108
	v_rcp_f32_e32 v109, v109
	v_rcp_f32_e32 v107, v107
	v_pk_mul_f32 v[98:99], v[102:103], v[98:99]
	v_pk_mul_f32 v[88:89], v[92:93], v[88:89]
	v_pk_mul_f32 v[96:97], v[96:97], v[108:109]
	v_pk_mul_f32 v[102:103], v[106:107], 1.0 op_sel_hi:[1,0]
	v_cvt_pk_bf16_f32 v106, v96, v97
	ds_read2_b32 v[96:97], v154 offset0:32 offset1:48
	v_pk_mul_f32 v[98:99], v[98:99], v[102:103]
	v_pk_mul_f32 v[90:91], v[94:95], v[90:91]
	v_cvt_pk_bf16_f32 v107, v98, v99
	v_add_u32_e32 v98, s11, v146
	s_waitcnt lgkmcnt(0)
	v_mul_f32_e32 v100, 0xbfb8aa3b, v96
	v_pk_mul_f32 v[102:103], v[94:95], v[100:101] op_sel_hi:[1,0]
	v_pk_mul_f32 v[108:109], v[92:93], v[100:101] op_sel_hi:[1,0]
	v_exp_f32_e32 v102, v102
	v_exp_f32_e32 v108, v108
	v_exp_f32_e32 v103, v103
	v_exp_f32_e32 v109, v109
	v_mad_i64_i32 v[98:99], s[20:21], v98, s38, v[112:113]
	v_lshl_add_u64 v[98:99], v[98:99], 0, v[114:115]
	global_store_dwordx4 v[98:99], v[104:107], off nt
	v_mul_f32_e32 v236, v96, v96
	v_rcp_f32_e32 v236, v236
	s_nop 0
	v_pk_fma_f32 v[98:99], v[102:103], v[236:237], v[236:237] op_sel_hi:[1,0,0]
	v_pk_fma_f32 v[102:103], v[108:109], v[236:237], v[236:237] op_sel_hi:[1,0,0]
	v_rcp_f32_e32 v98, v98
	v_rcp_f32_e32 v102, v102
	v_rcp_f32_e32 v103, v103
	v_rcp_f32_e32 v99, v99
	v_pk_mul_f32 v[82:83], v[86:87], v[82:83]
	v_pk_mul_f32 v[88:89], v[88:89], v[102:103]
	v_pk_mul_f32 v[92:93], v[86:87], v[100:101] op_sel_hi:[1,0]
	v_exp_f32_e32 v92, v92
	v_exp_f32_e32 v93, v93
	v_pk_mul_f32 v[90:91], v[90:91], v[98:99]
	v_pk_mul_f32 v[94:95], v[84:85], v[100:101] op_sel_hi:[1,0]
	v_cvt_pk_bf16_f32 v88, v88, v89
	v_exp_f32_e32 v94, v94
	v_exp_f32_e32 v95, v95
	v_cvt_pk_bf16_f32 v89, v90, v91
	v_pk_fma_f32 v[90:91], v[92:93], v[236:237], v[236:237] op_sel_hi:[1,0,0]
	v_pk_mul_f32 v[80:81], v[84:85], v[80:81]
	v_rcp_f32_e32 v90, v90
	v_rcp_f32_e32 v91, v91
	v_pk_fma_f32 v[92:93], v[94:95], v[236:237], v[236:237] op_sel_hi:[1,0,0]
	v_pk_mul_f32 v[74:75], v[78:79], v[74:75]
	v_rcp_f32_e32 v92, v92
	v_rcp_f32_e32 v93, v93
	v_pk_mul_f32 v[82:83], v[82:83], v[90:91]
	v_pk_mul_f32 v[72:73], v[76:77], v[72:73]
	v_cvt_pk_bf16_f32 v91, v82, v83
	v_mul_f32_e32 v82, 0xbfb8aa3b, v97
	v_pk_mul_f32 v[80:81], v[80:81], v[92:93]
	v_pk_mul_f32 v[84:85], v[78:79], v[82:83] op_sel_hi:[1,0]
	v_pk_mul_f32 v[86:87], v[76:77], v[82:83] op_sel_hi:[1,0]
	v_exp_f32_e32 v84, v84
	v_exp_f32_e32 v86, v86
	v_exp_f32_e32 v85, v85
	v_exp_f32_e32 v87, v87
	v_cvt_pk_bf16_f32 v90, v80, v81
	v_add_u32_e32 v80, s11, v147
	v_mul_f32_e32 v238, v97, v97
	v_rcp_f32_e32 v238, v238
	s_nop 0
	v_pk_fma_f32 v[84:85], v[84:85], v[238:239], v[238:239] op_sel_hi:[1,0,0]
	v_pk_fma_f32 v[86:87], v[86:87], v[238:239], v[238:239] op_sel_hi:[1,0,0]
	v_rcp_f32_e32 v84, v84
	v_rcp_f32_e32 v86, v86
	v_rcp_f32_e32 v87, v87
	v_rcp_f32_e32 v85, v85
	v_mad_i64_i32 v[80:81], s[20:21], v80, s38, v[112:113]
	v_lshl_add_u64 v[80:81], v[80:81], 0, v[114:115]
	global_store_dwordx4 v[80:81], v[88:91], off nt
	v_pk_mul_f32 v[74:75], v[74:75], v[84:85]
	v_pk_mul_f32 v[72:73], v[72:73], v[86:87]
	v_pk_mul_f32 v[76:77], v[70:71], v[82:83] op_sel_hi:[1,0]
	v_pk_mul_f32 v[78:79], v[68:69], v[82:83] op_sel_hi:[1,0]
	v_exp_f32_e32 v76, v76
	v_exp_f32_e32 v78, v78
	v_exp_f32_e32 v77, v77
	v_exp_f32_e32 v79, v79
	v_cvt_pk_bf16_f32 v72, v72, v73
	v_cvt_pk_bf16_f32 v73, v74, v75
	v_pk_fma_f32 v[74:75], v[76:77], v[238:239], v[238:239] op_sel_hi:[1,0,0]
	v_pk_fma_f32 v[76:77], v[78:79], v[238:239], v[238:239] op_sel_hi:[1,0,0]
	v_rcp_f32_e32 v74, v74
	v_rcp_f32_e32 v76, v76
	v_rcp_f32_e32 v77, v77
	v_rcp_f32_e32 v75, v75
	v_pk_mul_f32 v[64:65], v[68:69], v[64:65]
	v_pk_mul_f32 v[66:67], v[70:71], v[66:67]
	v_pk_mul_f32 v[64:65], v[64:65], v[76:77]
	v_pk_mul_f32 v[70:71], v[74:75], 1.0 op_sel_hi:[1,0]
	v_cvt_pk_bf16_f32 v74, v64, v65
	ds_read2_b32 v[64:65], v154 offset0:128 offset1:144
	v_pk_mul_f32 v[66:67], v[66:67], v[70:71]
	v_pk_mul_f32 v[56:57], v[60:61], v[56:57]
	v_cvt_pk_bf16_f32 v75, v66, v67
	v_add_u32_e32 v66, s11, v148
	s_waitcnt lgkmcnt(0)
	v_mul_f32_e32 v68, 0xbfb8aa3b, v64
	v_pk_mul_f32 v[70:71], v[62:63], v[68:69] op_sel_hi:[1,0]
	v_pk_mul_f32 v[76:77], v[60:61], v[68:69] op_sel_hi:[1,0]
	v_exp_f32_e32 v70, v70
	v_exp_f32_e32 v76, v76
	v_exp_f32_e32 v71, v71
	v_exp_f32_e32 v77, v77
	v_mad_i64_i32 v[66:67], s[20:21], v66, s38, v[112:113]
	v_lshl_add_u64 v[66:67], v[66:67], 0, v[114:115]
	global_store_dwordx4 v[66:67], v[72:75], off nt
	v_mul_f32_e32 v232, v64, v64
	v_rcp_f32_e32 v232, v232
	s_nop 0
	v_pk_fma_f32 v[66:67], v[70:71], v[232:233], v[232:233] op_sel_hi:[1,0,0]
	v_pk_fma_f32 v[70:71], v[76:77], v[232:233], v[232:233] op_sel_hi:[1,0,0]
	v_rcp_f32_e32 v66, v66
	v_rcp_f32_e32 v70, v70
	v_rcp_f32_e32 v71, v71
	v_rcp_f32_e32 v67, v67
	v_pk_mul_f32 v[58:59], v[62:63], v[58:59]
	v_pk_mul_f32 v[56:57], v[56:57], v[70:71]
	v_pk_mul_f32 v[60:61], v[54:55], v[68:69] op_sel_hi:[1,0]
	v_exp_f32_e32 v60, v60
	v_exp_f32_e32 v61, v61
	v_pk_mul_f32 v[58:59], v[58:59], v[66:67]
	v_pk_mul_f32 v[62:63], v[52:53], v[68:69] op_sel_hi:[1,0]
	v_cvt_pk_bf16_f32 v56, v56, v57
	v_exp_f32_e32 v62, v62
	v_exp_f32_e32 v63, v63
	v_cvt_pk_bf16_f32 v57, v58, v59
	v_pk_fma_f32 v[58:59], v[60:61], v[232:233], v[232:233] op_sel_hi:[1,0,0]
	v_pk_mul_f32 v[50:51], v[54:55], v[50:51]
	v_rcp_f32_e32 v58, v58
	v_rcp_f32_e32 v59, v59
	v_pk_fma_f32 v[60:61], v[62:63], v[232:233], v[232:233] op_sel_hi:[1,0,0]
	v_pk_mul_f32 v[48:49], v[52:53], v[48:49]
	v_rcp_f32_e32 v60, v60
	v_rcp_f32_e32 v61, v61
	v_pk_mul_f32 v[50:51], v[50:51], v[58:59]
	v_pk_mul_f32 v[42:43], v[46:47], v[42:43]
	v_cvt_pk_bf16_f32 v59, v50, v51
	v_mul_f32_e32 v50, 0xbfb8aa3b, v65
	v_pk_mul_f32 v[48:49], v[48:49], v[60:61]
	v_pk_mul_f32 v[52:53], v[46:47], v[50:51] op_sel_hi:[1,0]
	v_pk_mul_f32 v[54:55], v[44:45], v[50:51] op_sel_hi:[1,0]
	v_exp_f32_e32 v52, v52
	v_exp_f32_e32 v54, v54
	v_exp_f32_e32 v53, v53
	v_exp_f32_e32 v55, v55
	v_cvt_pk_bf16_f32 v58, v48, v49
	v_add_u32_e32 v48, 0x80, v116
	v_mul_f32_e32 v234, v65, v65
	v_rcp_f32_e32 v234, v234
	s_nop 0
	v_pk_fma_f32 v[52:53], v[52:53], v[234:235], v[234:235] op_sel_hi:[1,0,0]
	v_pk_fma_f32 v[54:55], v[54:55], v[234:235], v[234:235] op_sel_hi:[1,0,0]
	v_rcp_f32_e32 v52, v52
	v_rcp_f32_e32 v54, v54
	v_rcp_f32_e32 v55, v55
	v_rcp_f32_e32 v53, v53
	v_mad_i64_i32 v[48:49], s[20:21], v48, s38, v[112:113]
	v_lshl_add_u64 v[48:49], v[48:49], 0, v[114:115]
	global_store_dwordx4 v[48:49], v[56:59], off nt
	v_pk_mul_f32 v[40:41], v[44:45], v[40:41]
	v_pk_mul_f32 v[42:43], v[42:43], v[52:53]
	v_pk_mul_f32 v[40:41], v[40:41], v[54:55]
	v_pk_mul_f32 v[44:45], v[38:39], v[50:51] op_sel_hi:[1,0]
	v_pk_mul_f32 v[46:47], v[36:37], v[50:51] op_sel_hi:[1,0]
	v_exp_f32_e32 v44, v44
	v_exp_f32_e32 v46, v46
	v_exp_f32_e32 v45, v45
	v_exp_f32_e32 v47, v47
	v_cvt_pk_bf16_f32 v40, v40, v41
	v_cvt_pk_bf16_f32 v41, v42, v43
	v_pk_fma_f32 v[42:43], v[44:45], v[234:235], v[234:235] op_sel_hi:[1,0,0]
	v_pk_fma_f32 v[44:45], v[46:47], v[234:235], v[234:235] op_sel_hi:[1,0,0]
	v_rcp_f32_e32 v42, v42
	v_rcp_f32_e32 v44, v44
	v_rcp_f32_e32 v45, v45
	v_rcp_f32_e32 v43, v43
	v_pk_mul_f32 v[32:33], v[36:37], v[32:33]
	v_pk_mul_f32 v[34:35], v[38:39], v[34:35]
	v_pk_mul_f32 v[32:33], v[32:33], v[44:45]
	v_pk_mul_f32 v[38:39], v[42:43], 1.0 op_sel_hi:[1,0]
	v_cvt_pk_bf16_f32 v42, v32, v33
	ds_read2_b32 v[32:33], v154 offset0:160 offset1:176
	v_pk_mul_f32 v[34:35], v[34:35], v[38:39]
	v_pk_mul_f32 v[24:25], v[28:29], v[24:25]
	v_cvt_pk_bf16_f32 v43, v34, v35
	v_add_u32_e32 v34, 0x90, v116
	s_waitcnt lgkmcnt(0)
	v_mul_f32_e32 v36, 0xbfb8aa3b, v32
	v_pk_mul_f32 v[38:39], v[30:31], v[36:37] op_sel_hi:[1,0]
	v_pk_mul_f32 v[44:45], v[28:29], v[36:37] op_sel_hi:[1,0]
	v_exp_f32_e32 v38, v38
	v_exp_f32_e32 v44, v44
	v_exp_f32_e32 v39, v39
	v_exp_f32_e32 v45, v45
	v_mad_i64_i32 v[34:35], s[20:21], v34, s38, v[112:113]
	v_lshl_add_u64 v[34:35], v[34:35], 0, v[114:115]
	global_store_dwordx4 v[34:35], v[40:43], off nt
	v_mul_f32_e32 v236, v32, v32
	v_rcp_f32_e32 v236, v236
	s_nop 0
	v_pk_fma_f32 v[34:35], v[38:39], v[236:237], v[236:237] op_sel_hi:[1,0,0]
	v_pk_fma_f32 v[38:39], v[44:45], v[236:237], v[236:237] op_sel_hi:[1,0,0]
	v_rcp_f32_e32 v34, v34
	v_rcp_f32_e32 v38, v38
	v_rcp_f32_e32 v39, v39
	v_rcp_f32_e32 v35, v35
	v_pk_mul_f32 v[26:27], v[30:31], v[26:27]
	v_pk_mul_f32 v[24:25], v[24:25], v[38:39]
	v_pk_mul_f32 v[28:29], v[22:23], v[36:37] op_sel_hi:[1,0]
	v_exp_f32_e32 v28, v28
	v_exp_f32_e32 v29, v29
	v_pk_mul_f32 v[26:27], v[26:27], v[34:35]
	v_pk_mul_f32 v[30:31], v[20:21], v[36:37] op_sel_hi:[1,0]
	v_cvt_pk_bf16_f32 v24, v24, v25
	v_exp_f32_e32 v30, v30
	v_exp_f32_e32 v31, v31
	v_cvt_pk_bf16_f32 v25, v26, v27
	v_pk_fma_f32 v[26:27], v[28:29], v[236:237], v[236:237] op_sel_hi:[1,0,0]
	v_pk_mul_f32 v[18:19], v[22:23], v[18:19]
	v_rcp_f32_e32 v26, v26
	v_rcp_f32_e32 v27, v27
	v_pk_fma_f32 v[28:29], v[30:31], v[236:237], v[236:237] op_sel_hi:[1,0,0]
	v_pk_mul_f32 v[16:17], v[20:21], v[16:17]
	v_rcp_f32_e32 v28, v28
	v_rcp_f32_e32 v29, v29
	v_pk_mul_f32 v[18:19], v[18:19], v[26:27]
	v_pk_mul_f32 v[10:11], v[14:15], v[10:11]
	v_cvt_pk_bf16_f32 v27, v18, v19
	v_mul_f32_e32 v18, 0xbfb8aa3b, v33
	v_pk_mul_f32 v[16:17], v[16:17], v[28:29]
	v_pk_mul_f32 v[20:21], v[14:15], v[18:19] op_sel_hi:[1,0]
	v_pk_mul_f32 v[22:23], v[12:13], v[18:19] op_sel_hi:[1,0]
	v_exp_f32_e32 v20, v20
	v_exp_f32_e32 v22, v22
	v_exp_f32_e32 v21, v21
	v_exp_f32_e32 v23, v23
	v_cvt_pk_bf16_f32 v26, v16, v17
	v_add_u32_e32 v16, 0xa0, v116
	v_mul_f32_e32 v238, v33, v33
	v_rcp_f32_e32 v238, v238
	s_nop 0
	v_pk_fma_f32 v[20:21], v[20:21], v[238:239], v[238:239] op_sel_hi:[1,0,0]
	v_pk_fma_f32 v[22:23], v[22:23], v[238:239], v[238:239] op_sel_hi:[1,0,0]
	v_rcp_f32_e32 v20, v20
	v_rcp_f32_e32 v22, v22
	v_rcp_f32_e32 v23, v23
	v_rcp_f32_e32 v21, v21
	v_mad_i64_i32 v[16:17], s[20:21], v16, s38, v[112:113]
	v_lshl_add_u64 v[16:17], v[16:17], 0, v[114:115]
	global_store_dwordx4 v[16:17], v[24:27], off nt
	v_pk_mul_f32 v[8:9], v[12:13], v[8:9]
	v_pk_mul_f32 v[10:11], v[10:11], v[20:21]
	v_pk_mul_f32 v[8:9], v[8:9], v[22:23]
	v_pk_mul_f32 v[12:13], v[6:7], v[18:19] op_sel_hi:[1,0]
	v_pk_mul_f32 v[14:15], v[4:5], v[18:19] op_sel_hi:[1,0]
	v_exp_f32_e32 v12, v12
	v_exp_f32_e32 v14, v14
	v_exp_f32_e32 v13, v13
	v_exp_f32_e32 v15, v15
	v_cvt_pk_bf16_f32 v8, v8, v9
	v_cvt_pk_bf16_f32 v9, v10, v11
	v_pk_fma_f32 v[10:11], v[12:13], v[238:239], v[238:239] op_sel_hi:[1,0,0]
	v_pk_fma_f32 v[12:13], v[14:15], v[238:239], v[238:239] op_sel_hi:[1,0,0]
	v_rcp_f32_e32 v10, v10
	v_rcp_f32_e32 v12, v12
	v_rcp_f32_e32 v13, v13
	v_rcp_f32_e32 v11, v11
	v_pk_mul_f32 v[0:1], v[4:5], v[0:1]
	v_pk_mul_f32 v[2:3], v[6:7], v[2:3]
	v_pk_mul_f32 v[0:1], v[0:1], v[12:13]
	v_pk_mul_f32 v[6:7], v[10:11], 1.0 op_sel_hi:[1,0]
	v_cvt_pk_bf16_f32 v10, v0, v1
	v_add_u32_e32 v0, 0xb0, v116
	v_pk_mul_f32 v[2:3], v[2:3], v[6:7]
	v_mad_i64_i32 v[0:1], s[20:21], v0, s38, v[112:113]
	v_cvt_pk_bf16_f32 v11, v2, v3
	v_lshl_add_u64 v[0:1], v[0:1], 0, v[114:115]
	s_andn2_b64 vcc, exec, s[0:1]
	s_mov_b64 s[0:1], -1
	global_store_dwordx4 v[0:1], v[8:11], off nt
	s_cbranch_vccnz .LBB0_701
	s_andn2_b64 vcc, exec, s[4:5]
	s_cbranch_vccnz .LBB0_700
	s_barrier
	s_branch .LBB0_700
